# placement decision taken locally from the eight half masks after the second grid barrier; no check (and no counter) on the critical point at the end of the first P1 pass
# baseline (speedup 1.0000x reference)
; #define LAS __attribute__((address_space(3)))
; #define LANE_SETUP() int tid_ = threadIdx.x; asm volatile("" : "+v"(tid_)); const int tid = tid_, lane = tid & 63; (void)lane
; #define SEAM(k) do { if ((k) < 2) xcd_barrier(bar); else xcd_barrier(barg); } while (0)
; __global__ void __launch_bounds__(NWAVES * 64, 2) fwd(Args a) {
;     ...
;     SEAM(0);
;     for (int rep = 0; rep <= PROBE_REPS(1); ++rep) { const float asc = rep ? 0.f : 1.f; (void)asc;
;     if (IN(1)) {
;         LANE_SETUP();
;         LAS float* scr = (LAS float*)(lds + RING_OFF + wave * 16384);
;         constexpr int I0 = 16 * 64, I1 = I0 + 8 * 32, I2 = I1 + 16 * 176, I4 = I2 + 44 * 32, I5 = I4 + 4 * 16 * 16, I6 = I5 + 88, I7 = I6 + NBATCH * 16;
;         for (int it = gw; it < I7; it += NGW) {
.Lp1_released:
.Lp1_poll_done:
	s_or_b64 exec, exec, s[0:1]
	s_barrier
	s_mov_b32 s99, 1
	s_cmpk_lt_i32 s77, 0x1a78
	s_cbranch_scc0 .Lp1_rows
	s_mov_b32 s33, s77
	s_mov_b32 s4, s98
	s_lshl_b32 s13, s77, 6
	s_branch .LBB0_68

; #define PG8_STAGE(bufoff, gbase, voff) do { _Pragma("unroll") for (int _i = 0; _i < 2; ++_i) \
;         __builtin_amdgcn_global_load_lds((const unsigned*)((const char*)(gbase) + (voff)[_i]), (PG8_LAS unsigned*)(lds + (bufoff) + ldsw + _i * 8192), 16, 0, 0); } while (0)
; #define PG8_WAIT_V(n) asm volatile("s_waitcnt vmcnt(" #n ")" ::: "memory")
; #define PG8_BAR __builtin_amdgcn_s_barrier()
; template <class Epi, class Sched, bool ALIGN_EPI = false, bool SP2 = false>
; __device__ __forceinline__ void gemm_phase(PG8_LAS unsigned char* lds, const Gemm g, const Sched& S, const Epi& E, volatile PG8_LAS unsigned* sw = nullptr) {
;     ...
;     for (int i = 0; i < 2; ++i) { int R, C; stage_rc(tid * 16 + i * 8192, R, C); const int Rb = Epi::PERM ? ((R & ~31) + perm32(R & 31)) : R;
;         const int Ra = Epi::PERMA ? ((R & 64) + 4 * (R & 15) + ((R >> 4) & 3)) : R;
;         voffA[i] = (unsigned)(Ra * BK + C) * 2u; voffB[i] = (unsigned)(Rb * BK + C) * 2u; }
;     const size_t kstep = (size_t)(BM * BK * 2);
;     const size_t hstep = (size_t)HALF * BK * 2;
;     const size_t tstep = (size_t)K * BM * 2;
;     const unsigned ldsw = (unsigned)wid * 1024u;
;     const int aoff = lds_byte(wr * 64 + fr, fq * 8), boff = lds_byte(wc * 32 + fr, fq * 8);
;     ...
;     const char* cA = (const char*)g.A + (size_t)cur.pm * tstep; const char* cB = (const char*)g.Bt + (size_t)cur.pn * tstep;
;     S.a_ready(cur);
;     if constexpr (SP2) {
;         PG8_STAGE(PG8_SB(0, 0), cB, voffB); PG8_STAGE(PG8_SB(0, 1), cB + hstep, voffB); PG8_STAGE(PG8_SA(0, 0), cA, voffA); PG8_STAGE(PG8_SA(0, 1), cA + hstep, voffA);
;         if (wr == 1) PG8_BAR;
;         PG8_WAIT_V(2); PG8_BAR;
;         PG8_STAGE(PG8_SB(1, 0), cB + kstep, voffB); PG8_STAGE(PG8_SA(1, 0), cA + kstep, voffA); PG8_STAGE(PG8_SB(1, 1), cB + hstep + kstep, voffB);
.LBB0_153:
	v_writelane_b32 v250, s70, 40
	s_nop 1
	v_writelane_b32 v250, s71, 41
	v_writelane_b32 v250, s68, 42
	s_nop 1
	v_writelane_b32 v250, s69, 43
	s_or_b64 exec, exec, s[0:1]
	s_and_saveexec_b64 s[4:5], s[80:81]
	v_mov_b32_e32 v1, 0x18000
	global_load_dwordx4 v[2:5], v1, s[60:61] sc1
	global_load_dwordx4 v[6:9], v1, s[60:61] offset:16 sc1
	s_waitcnt vmcnt(0)
	v_add_u32_e32 v11, -1, v2
	v_and_b32_e32 v10, v11, v2
	v_add_u32_e32 v11, -1, v3
	v_and_or_b32 v10, v11, v3, v10
	v_add_u32_e32 v11, -1, v4
	v_and_or_b32 v10, v11, v4, v10
	v_add_u32_e32 v11, -1, v5
	v_and_or_b32 v10, v11, v5, v10
	v_add_u32_e32 v11, -1, v6
	v_and_or_b32 v10, v11, v6, v10
	v_add_u32_e32 v11, -1, v7
	v_and_or_b32 v10, v11, v7, v10
	v_add_u32_e32 v11, -1, v8
	v_and_or_b32 v10, v11, v8, v10
	v_add_u32_e32 v11, -1, v9
	v_and_or_b32 v10, v11, v9, v10
	s_nop 0
	v_readfirstlane_b32 s100, v10
	s_or_b64 exec, exec, s[4:5]
	v_readlane_b32 s3, v250, 10
	s_mul_i32 s0, s3, 0x7000000
	s_add_u32 s0, s60, s0
	s_addc_u32 s1, s61, 0
	s_add_u32 s16, s0, 0x2800000
	s_addc_u32 s17, s1, 0
	s_ashr_i32 s97, s2, 3
	s_and_b32 s18, s2, 1
	s_ashr_i32 s62, s83, 3
	s_add_u32 s91, s60, 0x100000
	s_addc_u32 s92, s61, 0
	s_add_u32 s24, s0, 0x3800000
	s_addc_u32 s25, s1, 0
	s_lshl_b32 s60, s18, 4
	s_lshl_b32 s61, s3, 13
	v_mov_b32_e32 v2, v0
	s_waitcnt lgkmcnt(0)
	s_barrier
	s_cmpk_lt_i32 s97, 0x80
	s_nop 0
	v_readfirstlane_b32 s6, v2
	s_cbranch_scc0 .LBB0_173
	v_lshlrev_b32_e32 v1, 4, v2
	v_add_u32_e32 v4, 0x2000, v1
	v_ashrrev_i32_e32 v3, 31, v4
	v_lshrrev_b32_e32 v3, 22, v3
	v_add_u32_e32 v3, v4, v3
	v_ashrrev_i32_e32 v3, 10, v3
	v_mul_i32_i24_e32 v5, 0x400, v3
	v_sub_u32_e32 v4, v4, v5
	v_lshrrev_b32_e32 v5, 4, v4
	v_bitop3_b32 v5, v5, v4, 32 bitop3:0x6c
	v_ashrrev_i32_e32 v4, 31, v5
	v_lshrrev_b32_e32 v4, 26, v4
	v_add_u32_e32 v6, v5, v4
	v_lshlrev_b32_e32 v7, 3, v3
	v_ashrrev_i32_e32 v4, 6, v6
	v_and_b32_e32 v7, -16, v7
	v_add_u32_e32 v7, v4, v7
	v_and_b32_e32 v8, 3, v4
	s_mov_b32 s8, 0x1ffffe0
	v_lshrrev_b32_e32 v9, 2, v7
	v_lshlrev_b32_e32 v10, 1, v7
	v_and_or_b32 v8, v7, s8, v8
	v_and_b32_e32 v9, 4, v9
	v_and_b32_e32 v10, 24, v10
	v_and_b32_e32 v6, 0xc0, v6
	v_or3_b32 v8, v8, v9, v10
	v_sub_u32_e32 v5, v5, v6
	v_mov_b32_e32 v10, 1
	v_lshlrev_b32_e32 v9, 5, v3
	v_ashrrev_i16_sdwa v5, v10, sext(v5) dst_sel:DWORD dst_unused:UNUSED_PAD src0_sel:DWORD src1_sel:BYTE_0
	v_and_b32_e32 v9, 32, v9
	v_bfe_i32 v5, v5, 0, 16
	s_ashr_i32 s0, s97, 31
	v_add_lshl_u32 v6, v9, v5, 1
	s_lshr_b32 s0, s0, 26
	v_lshl_add_u32 v130, v8, 7, v6
	v_lshl_add_u32 v132, v7, 7, v6
	v_bfe_i32 v6, v2, 27, 1
	s_add_i32 s0, s97, s0
	v_lshrrev_b32_e32 v6, 22, v6
	s_ashr_i32 s1, s0, 6
	s_andn2_b32 s0, s0, 63
	v_add_u32_e32 v6, v1, v6
	s_sub_i32 s0, s97, s0
	s_lshl_b32 s1, s1, 3
	v_and_b32_e32 v6, 0xfffffc00, v6
	s_add_i32 s1, s1, s60
	s_and_b32 s2, s0, 7
	v_sub_u32_e32 v1, v1, v6
	s_or_b32 s46, s1, s2
	s_ashr_i32 s2, s0, 3
	v_lshrrev_b32_e32 v6, 4, v1
	v_ashrrev_i32_e32 v7, 31, v2
	s_ashr_i32 s47, s46, 31
	s_ashr_i32 s3, s2, 31
	v_bitop3_b32 v1, v6, v1, 32 bitop3:0x6c
	v_lshrrev_b32_e32 v7, 26, v7
	s_lshl_b64 s[0:1], s[46:47], 19
	s_lshl_b64 s[4:5], s[2:3], 19
	v_ashrrev_i32_e32 v6, 31, v1
	v_add_u32_e32 v7, v2, v7
	s_add_u32 s50, s14, s4
	v_lshrrev_b32_e32 v6, 26, v6
	v_ashrrev_i32_e32 v7, 6, v7
	s_addc_u32 s51, s15, s5
	v_add_u32_e32 v8, v1, v6
	v_lshlrev_b32_e32 v9, 3, v7
	s_add_u32 s48, s16, s0
	v_ashrrev_i32_e32 v6, 6, v8
	v_and_b32_e32 v9, -16, v9
	s_addc_u32 s49, s17, s1
	s_ashr_i32 s3, s6, 6
	v_add_u32_e32 v9, v6, v9
	s_ashr_i32 s7, s6, 8
	s_lshl_b32 s19, s3, 10
	v_and_b32_e32 v11, 3, v6
	v_lshrrev_b32_e32 v12, 2, v9
	v_lshlrev_b32_e32 v13, 1, v9
	v_and_b32_e32 v8, 0xc0, v8
	s_add_u32 s0, s48, 0x4000
	v_and_or_b32 v11, v9, s8, v11
	v_and_b32_e32 v12, 4, v12
	v_and_b32_e32 v13, 24, v13
	v_sub_u32_e32 v1, v1, v8
	s_addc_u32 s1, s49, 0
	v_or3_b32 v11, v11, v12, v13
	v_lshlrev_b32_e32 v12, 5, v7
	v_ashrrev_i16_sdwa v1, v10, sext(v1) dst_sel:DWORD dst_unused:UNUSED_PAD src0_sel:DWORD src1_sel:BYTE_0
	s_add_u32 s4, s50, 0x4000
	v_and_b32_e32 v12, 32, v12
	v_bfe_i32 v8, v1, 0, 16
	s_addc_u32 s5, s51, 0
	v_add_lshl_u32 v1, v12, v8, 1
	s_add_i32 s20, s19, 0
	v_lshl_add_u32 v134, v11, 7, v1
	s_add_i32 m0, s20, 0x10000
	v_lshl_add_u32 v136, v9, 7, v1
	global_load_lds_dwordx4 v134, s[50:51]
	s_add_i32 m0, s20, 0x12000
	s_add_i32 s21, s20, 0x2000
	global_load_lds_dwordx4 v130, s[50:51]
	s_add_i32 m0, s20, 0x14000
	s_add_i32 s22, s20, 0x4000
	global_load_lds_dwordx4 v134, s[4:5]
	s_add_i32 m0, s20, 0x16000
	s_add_i32 s23, s20, 0x6000
	global_load_lds_dwordx4 v130, s[4:5]
	s_mov_b32 m0, s20
	v_mov_b32_e32 v135, 0
	global_load_lds_dwordx4 v136, s[48:49]
	s_mov_b32 m0, s21
	s_cmp_eq_u32 s7, 1
	global_load_lds_dwordx4 v132, s[48:49]
	s_mov_b32 m0, s22
	v_mov_b32_e32 v131, v135
	global_load_lds_dwordx4 v136, s[0:1]
	s_mov_b32 m0, s23
	v_mov_b32_e32 v137, v135
	global_load_lds_dwordx4 v132, s[0:1]
	s_cselect_b64 s[4:5], -1, 0
	s_cmp_lg_u32 s7, 1
	v_mov_b32_e32 v133, v135
	s_cbranch_scc1 .LBB0_156
	s_barrier
